# LN1 row loop de-serialised: gamma/beta hoisted, scale/shift loads issued before next-row prefetch, L2 touch of row u+2, counted vmcnt
# speedup vs baseline: 1.0254x; 1.0254x over previous
.LBB0_201:
	v_readlane_b32 s14, v255, 3
	v_readlane_b32 s15, v255, 4
	s_mov_b64 s[6:7], s[0:1]
	s_mov_b64 s[4:5], s[0:1]
	s_waitcnt lgkmcnt(0)
	s_mov_b64 s[8:9], s[0:1]
	s_mov_b64 s[10:11], s[0:1]
	s_mov_b64 s[12:13], s[0:1]
	v_mov_b32_e32 v0, v254
	s_andn2_b64 vcc, exec, s[14:15]
	s_cbranch_vccnz .LBB0_210
	s_load_dwordx2 s[14:15], s[6:7], 0x118
	v_and_b32_e32 v5, 63, v0
	v_ashrrev_i32_e32 v0, 6, v0
	v_readlane_b32 s2, v255, 23
	v_lshlrev_b32_e32 v2, 4, v5
	v_mov_b32_e32 v3, v149
	v_add_u32_e32 v148, s2, v0
	v_lshlrev_b64 v[0:1], 12, v[148:149]
	s_waitcnt lgkmcnt(0)
	v_lshl_add_u64 v[0:1], s[14:15], 0, v[0:1]
	v_lshl_add_u64 v[0:1], v[0:1], 0, v[2:3]
	global_load_dwordx4 v[16:19], v[0:1], off offset:3072
	global_load_dwordx4 v[20:23], v[0:1], off offset:2048
	global_load_dwordx4 v[24:27], v[0:1], off offset:1024
	global_load_dwordx4 v[28:31], v[0:1], off
	s_load_dwordx2 s[4:5], s[4:5], 0xe8
	s_nop 0
	s_load_dwordx2 s[16:17], s[10:11], 0x120
	s_load_dwordx2 s[20:21], s[8:9], 0xf0
	s_nop 0
	s_load_dwordx2 s[10:11], s[12:13], 0x120
	s_mul_i32 s26, s82, 0xd800
	s_lshl_b64 s[8:9], s[26:27], 2
	s_waitcnt lgkmcnt(0)
	s_add_u32 s8, s16, s8
	s_addc_u32 s9, s17, s9
	s_add_u32 s10, s10, 0x110c1000
	s_addc_u32 s11, s11, 0
	s_lshl_b32 s26, s82, 10
	s_lshl_b64 s[12:13], s[26:27], 2
	s_add_u32 s20, s20, s12
	s_addc_u32 s21, s21, s13
	s_add_u32 s22, s4, s12
	s_addc_u32 s23, s5, s13
	s_cmp_lg_u64 s[16:17], 0
	v_readlane_b32 s16, v255, 5
	v_lshlrev_b32_e32 v32, 2, v5
	s_cselect_b64 s[12:13], -1, 0
	v_readlane_b32 s17, v255, 6
	s_add_u32 s14, s14, s16
	v_or_b32_e32 v0, 0x100, v32
	v_or_b32_e32 v4, 0x200, v32
	v_or_b32_e32 v6, 0x300, v32
	s_addc_u32 s15, s15, s17
	v_xor_b32_e32 v33, 64, v32
	v_xor_b32_e32 v60, 0x80, v32
	v_cmp_eq_u32_e64 s[4:5], 0, v5
	v_lshl_add_u64 v[34:35], s[22:23], 0, v[2:3]
	v_lshl_add_u64 v[36:37], s[20:21], 0, v[2:3]
	v_lshl_add_u64 v[38:39], s[14:15], 0, v[2:3]
	global_load_dwordx4 v[80:83], v[34:35], off
	global_load_dwordx4 v[84:87], v[34:35], off offset:1024
	global_load_dwordx4 v[88:91], v[34:35], off offset:2048
	global_load_dwordx4 v[92:95], v[34:35], off offset:3072
	global_load_dwordx4 v[96:99], v[36:37], off
	global_load_dwordx4 v[100:103], v[36:37], off offset:1024
	global_load_dwordx4 v[104:107], v[36:37], off offset:2048
	global_load_dwordx4 v[108:111], v[36:37], off offset:3072
	v_and_b32_e32 v74, 31, v5
	v_lshlrev_b32_e32 v74, 7, v74
	v_sub_u32_e32 v74, v74, v2
	v_ashrrev_i32_e32 v75, 31, v74
	v_lshl_add_u64 v[74:75], v[38:39], 0, v[74:75]
	s_waitcnt vmcnt(0)
	v_lshlrev_b32_e32 v40, 2, v0
	v_lshlrev_b32_e32 v42, 2, v4
	v_lshlrev_b32_e32 v44, 2, v6
	v_mov_b32_e32 v46, v148
	v_readlane_b32 s2, v255, 0
	s_branch .LBB0_204
.LBB0_203:
	v_add_u32_e32 v46, s90, v46
	s_and_b64 vcc, exec, s[20:21]
	s_cbranch_vccnz .LBB0_210
	s_waitcnt vmcnt(6)
	v_mov_b64_e32 v[30:31], v[2:3]
	v_mov_b64_e32 v[28:29], v[0:1]
	v_mov_b64_e32 v[26:27], v[6:7]
	v_mov_b64_e32 v[24:25], v[4:5]
	v_mov_b64_e32 v[22:23], v[10:11]
	v_mov_b64_e32 v[20:21], v[8:9]
	v_mov_b64_e32 v[18:19], v[14:15]
	v_mov_b64_e32 v[16:17], v[12:13]
.LBB0_204:
	s_add_i32 s2, s2, s18
	s_cmpk_gt_i32 s2, 0x17ff
	v_ashrrev_i32_e32 v47, 31, v46
	s_cselect_b64 s[20:21], -1, 0
	v_lshlrev_b64 v[48:49], 10, v[46:47]
	v_add_u32_e32 v64, 0xffffe000, v46
	v_lshrrev_b32_e32 v64, 11, v64
	v_add_u32_e32 v64, 1, v64
	v_cmp_lt_i32_e32 vcc, s34, v46
	s_nop 1
	v_cndmask_b32_e32 v66, 0, v64, vcc
	v_mov_b64_e32 v[64:65], s[8:9]
	v_mad_u64_u32 v[64:65], s[14:15], v66, s35, v[64:65]
	s_mov_b64 s[14:15], 0x3000
	s_nop 0
	v_lshl_add_u64 v[66:67], v[64:65], 0, s[14:15]
	s_mov_b64 s[14:15], 0x4000
	v_lshl_add_u64 v[68:69], v[64:65], 0, s[14:15]
	v_lshlrev_b32_e32 v148, 2, v32
	v_mov_b32_e32 v41, v149
	v_mov_b32_e32 v43, v149
	v_mov_b32_e32 v45, v149
	v_lshl_add_u64 v[70:71], v[68:69], 0, v[148:149]
	global_load_dwordx4 v[112:115], v[70:71], off
	v_lshl_add_u64 v[70:71], v[68:69], 0, v[40:41]
	global_load_dwordx4 v[116:119], v[70:71], off
	v_lshl_add_u64 v[70:71], v[68:69], 0, v[42:43]
	global_load_dwordx4 v[120:123], v[70:71], off
	v_lshl_add_u64 v[70:71], v[68:69], 0, v[44:45]
	global_load_dwordx4 v[124:127], v[70:71], off
	v_lshl_add_u64 v[70:71], v[66:67], 0, v[148:149]
	global_load_dwordx4 v[128:131], v[70:71], off
	v_lshl_add_u64 v[70:71], v[66:67], 0, v[40:41]
	global_load_dwordx4 v[132:135], v[70:71], off
	v_lshl_add_u64 v[70:71], v[66:67], 0, v[42:43]
	global_load_dwordx4 v[136:139], v[70:71], off
	v_lshl_add_u64 v[70:71], v[66:67], 0, v[44:45]
	global_load_dwordx4 v[140:143], v[70:71], off
	s_and_b64 vcc, exec, s[20:21]
	s_cbranch_vccnz .Lln1_nopf
	v_lshl_add_u64 v[12:13], v[48:49], 2, v[38:39]
	v_lshl_add_u64 v[70:71], v[48:49], 2, v[74:75]
	global_load_dwordx4 v[0:3], v[12:13], off
	global_load_dwordx4 v[4:7], v[12:13], off offset:1024
	global_load_dwordx4 v[8:11], v[12:13], off offset:2048
	s_nop 0
	global_load_dwordx4 v[12:15], v[12:13], off offset:3072
	s_add_i32 s14, s2, s18
	s_cmpk_gt_i32 s14, 0x17ff
	s_cselect_b32 s14, 0, s16
	s_cselect_b32 s15, 0, s17
	v_lshl_add_u64 v[70:71], v[70:71], 0, s[14:15]
	global_load_dword v150, v[70:71], off

.LBB0_208:
	s_or_b64 exec, exec, s[14:15]
	s_load_dwordx2 s[14:15], s[6:7], 0x120
	s_and_b64 vcc, exec, s[20:21]
	s_cbranch_vccnz .Lln1_wl
	s_waitcnt vmcnt(6)
	s_branch .Lln1_wd
.Lln1_wl:
	s_waitcnt vmcnt(1)
.Lln1_wd:
	v_mov_b32_e32 v26, v57
	v_lshlrev_b32_e32 v148, 1, v32
	s_waitcnt lgkmcnt(0)
	v_lshl_add_u64 v[64:65], v[48:49], 1, s[14:15]
	s_mov_b64 s[14:15], 0xe0c1000
	v_lshl_add_u64 v[64:65], v[64:65], 0, v[148:149]
	v_lshl_add_u64 v[64:65], v[64:65], 0, s[14:15]
	v_pk_mul_f32 v[20:21], v[54:55], v[26:27] op_sel_hi:[1,0]
	v_pk_mul_f32 v[22:23], v[58:59], v[26:27] op_sel_hi:[1,0]
	v_pk_add_f32 v[24:25], v[112:113], 1.0 op_sel_hi:[1,0]
	v_pk_add_f32 v[62:63], v[114:115], 1.0 op_sel_hi:[1,0]
	v_pk_fma_f32 v[20:21], v[20:21], v[80:81], v[96:97]
	v_pk_fma_f32 v[22:23], v[22:23], v[82:83], v[98:99]
	v_pk_fma_f32 v[20:21], v[20:21], v[24:25], v[128:129]
	v_pk_fma_f32 v[22:23], v[22:23], v[62:63], v[130:131]
	v_cvt_pk_bf16_f32 v72, v20, v21
	v_cvt_pk_bf16_f32 v73, v22, v23
	global_store_dwordx2 v[64:65], v[72:73], off
	v_pk_mul_f32 v[20:21], v[50:51], v[26:27] op_sel_hi:[1,0]
	v_pk_mul_f32 v[22:23], v[52:53], v[26:27] op_sel_hi:[1,0]
	v_pk_add_f32 v[24:25], v[116:117], 1.0 op_sel_hi:[1,0]
	v_pk_add_f32 v[62:63], v[118:119], 1.0 op_sel_hi:[1,0]
	v_pk_fma_f32 v[20:21], v[20:21], v[84:85], v[100:101]
	v_pk_fma_f32 v[22:23], v[22:23], v[86:87], v[102:103]
	v_pk_fma_f32 v[20:21], v[20:21], v[24:25], v[132:133]
	v_pk_fma_f32 v[22:23], v[22:23], v[62:63], v[134:135]
	v_cvt_pk_bf16_f32 v72, v20, v21
	v_cvt_pk_bf16_f32 v73, v22, v23
	global_store_dwordx2 v[64:65], v[72:73], off offset:512
	v_pk_mul_f32 v[20:21], v[28:29], v[26:27] op_sel_hi:[1,0]
	v_pk_mul_f32 v[22:23], v[30:31], v[26:27] op_sel_hi:[1,0]
	v_pk_add_f32 v[24:25], v[120:121], 1.0 op_sel_hi:[1,0]
	v_pk_add_f32 v[62:63], v[122:123], 1.0 op_sel_hi:[1,0]
	v_pk_fma_f32 v[20:21], v[20:21], v[88:89], v[104:105]
	v_pk_fma_f32 v[22:23], v[22:23], v[90:91], v[106:107]
	v_pk_fma_f32 v[20:21], v[20:21], v[24:25], v[136:137]
	v_pk_fma_f32 v[22:23], v[22:23], v[62:63], v[138:139]
	v_cvt_pk_bf16_f32 v72, v20, v21
	v_cvt_pk_bf16_f32 v73, v22, v23
	global_store_dwordx2 v[64:65], v[72:73], off offset:1024
	v_pk_mul_f32 v[20:21], v[16:17], v[26:27] op_sel_hi:[1,0]
	v_pk_mul_f32 v[22:23], v[18:19], v[26:27] op_sel_hi:[1,0]
	v_pk_add_f32 v[24:25], v[124:125], 1.0 op_sel_hi:[1,0]
	v_pk_add_f32 v[62:63], v[126:127], 1.0 op_sel_hi:[1,0]
	v_pk_fma_f32 v[20:21], v[20:21], v[92:93], v[108:109]
	v_pk_fma_f32 v[22:23], v[22:23], v[94:95], v[110:111]
	v_pk_fma_f32 v[20:21], v[20:21], v[24:25], v[140:141]
	v_pk_fma_f32 v[22:23], v[22:23], v[62:63], v[142:143]
	v_cvt_pk_bf16_f32 v72, v20, v21
	v_cvt_pk_bf16_f32 v73, v22, v23
	global_store_dwordx2 v[64:65], v[72:73], off offset:1536
	s_branch .LBB0_203
